# NA (layer 0) tile loop: QK with all K fragments read up front, 16-instr max tree, exp/cvt interleaved with PV MFMAs (block replacements inside hipcc's loop)
# baseline (speedup 1.0000x reference)
.LBB0_279:
	v_add3_u32 v94, s10, v113, v114
	v_add_u32_e32 v95, s10, v115
	ds_read_b64_tr_b16 v[148:149], v94 offset:8192
	ds_read_b64_tr_b16 v[150:151], v94 offset:9216
	ds_read_b64_tr_b16 v[152:153], v95 offset:8192
	ds_read_b64_tr_b16 v[154:155], v95 offset:9216
	ds_read_b64_tr_b16 v[156:157], v94 offset:10240
	ds_read_b64_tr_b16 v[158:159], v94 offset:11264
	ds_read_b64_tr_b16 v[160:161], v95 offset:10240
	ds_read_b64_tr_b16 v[162:163], v95 offset:11264
	ds_read_b64_tr_b16 v[164:165], v94 offset:12288
	ds_read_b64_tr_b16 v[166:167], v94 offset:13312
	ds_read_b64_tr_b16 v[168:169], v95 offset:12288
	ds_read_b64_tr_b16 v[170:171], v95 offset:13312
	v_sub_f32_e32 v34, v34, v101
	v_sub_f32_e32 v35, v35, v101
	v_sub_f32_e32 v36, v36, v101
	v_sub_f32_e32 v37, v37, v101
	v_sub_f32_e32 v38, v38, v101
	v_sub_f32_e32 v39, v39, v101
	v_sub_f32_e32 v40, v40, v101
	v_sub_f32_e32 v41, v41, v101
	v_exp_f32_e32 v34, v34
	v_exp_f32_e32 v35, v35
	v_exp_f32_e32 v36, v36
	v_exp_f32_e32 v37, v37
	v_exp_f32_e32 v38, v38
	v_exp_f32_e32 v39, v39
	v_exp_f32_e32 v40, v40
	v_exp_f32_e32 v41, v41
	v_cvt_pk_bf16_f32 v180, v34, v35
	v_cvt_pk_bf16_f32 v181, v36, v37
	v_cvt_pk_bf16_f32 v182, v38, v39
	v_cvt_pk_bf16_f32 v183, v40, v41
	v_add_f32_e32 v130, v34, v35
	v_add_f32_e32 v131, v36, v37
	v_add_f32_e32 v130, v130, v38
	v_add_f32_e32 v131, v131, v39
	v_add_f32_e32 v130, v130, v40
	v_add_f32_e32 v131, v131, v41
	v_add_f32_e32 v97, v97, v130
	v_add_f32_e32 v97, v97, v131
	s_waitcnt lgkmcnt(10)
	v_mfma_f32_32x32x16_bf16 v[18:33], v[148:151], v[180:183], v[18:33]
	s_waitcnt lgkmcnt(8)
	v_mfma_f32_32x32x16_bf16 v[2:17], v[152:155], v[180:183], v[2:17]
	ds_read_b64_tr_b16 v[172:173], v94 offset:14336
	ds_read_b64_tr_b16 v[174:175], v94 offset:15360
	ds_read_b64_tr_b16 v[176:177], v95 offset:14336
	ds_read_b64_tr_b16 v[178:179], v95 offset:15360
	v_sub_f32_e32 v42, v42, v101
	v_sub_f32_e32 v43, v43, v101
	v_sub_f32_e32 v44, v44, v101
	v_sub_f32_e32 v45, v45, v101
	v_sub_f32_e32 v46, v46, v101
	v_sub_f32_e32 v47, v47, v101
	v_sub_f32_e32 v48, v48, v101
	v_sub_f32_e32 v49, v49, v101
	v_exp_f32_e32 v42, v42
	v_exp_f32_e32 v43, v43
	v_exp_f32_e32 v44, v44
	v_exp_f32_e32 v45, v45
	v_exp_f32_e32 v46, v46
	v_exp_f32_e32 v47, v47
	v_exp_f32_e32 v48, v48
	v_exp_f32_e32 v49, v49
	v_cvt_pk_bf16_f32 v184, v42, v43
	v_cvt_pk_bf16_f32 v185, v44, v45
	v_cvt_pk_bf16_f32 v186, v46, v47
	v_cvt_pk_bf16_f32 v187, v48, v49
	v_add_f32_e32 v130, v42, v43
	v_add_f32_e32 v131, v44, v45
	v_add_f32_e32 v130, v130, v46
	v_add_f32_e32 v131, v131, v47
	v_add_f32_e32 v130, v130, v48
	v_add_f32_e32 v131, v131, v49
	v_add_f32_e32 v97, v97, v130
	v_add_f32_e32 v97, v97, v131
	s_waitcnt lgkmcnt(10)
	v_mfma_f32_32x32x16_bf16 v[18:33], v[156:159], v[184:187], v[18:33]
	s_waitcnt lgkmcnt(8)
	v_mfma_f32_32x32x16_bf16 v[2:17], v[160:163], v[184:187], v[2:17]
	v_sub_f32_e32 v50, v50, v101
	v_sub_f32_e32 v51, v51, v101
	v_sub_f32_e32 v52, v52, v101
	v_sub_f32_e32 v53, v53, v101
	v_sub_f32_e32 v54, v54, v101
	v_sub_f32_e32 v55, v55, v101
	v_sub_f32_e32 v56, v56, v101
	v_sub_f32_e32 v57, v57, v101
	v_exp_f32_e32 v50, v50
	v_exp_f32_e32 v51, v51
	v_exp_f32_e32 v52, v52
	v_exp_f32_e32 v53, v53
	v_exp_f32_e32 v54, v54
	v_exp_f32_e32 v55, v55
	v_exp_f32_e32 v56, v56
	v_exp_f32_e32 v57, v57
	v_cvt_pk_bf16_f32 v188, v50, v51
	v_cvt_pk_bf16_f32 v189, v52, v53
	v_cvt_pk_bf16_f32 v190, v54, v55
	v_cvt_pk_bf16_f32 v191, v56, v57
	v_add_f32_e32 v130, v50, v51
	v_add_f32_e32 v131, v52, v53
	v_add_f32_e32 v130, v130, v54
	v_add_f32_e32 v131, v131, v55
	v_add_f32_e32 v130, v130, v56
	v_add_f32_e32 v131, v131, v57
	v_add_f32_e32 v97, v97, v130
	v_add_f32_e32 v97, v97, v131
	s_waitcnt lgkmcnt(6)
	v_mfma_f32_32x32x16_bf16 v[18:33], v[164:167], v[188:191], v[18:33]
	s_waitcnt lgkmcnt(4)
	v_mfma_f32_32x32x16_bf16 v[2:17], v[168:171], v[188:191], v[2:17]
	v_sub_f32_e32 v58, v58, v101
	v_sub_f32_e32 v59, v59, v101
	v_sub_f32_e32 v60, v60, v101
	v_sub_f32_e32 v61, v61, v101
	v_sub_f32_e32 v62, v62, v101
	v_sub_f32_e32 v63, v63, v101
	v_sub_f32_e32 v64, v64, v101
	v_sub_f32_e32 v65, v65, v101
	v_exp_f32_e32 v58, v58
	v_exp_f32_e32 v59, v59
	v_exp_f32_e32 v60, v60
	v_exp_f32_e32 v61, v61
	v_exp_f32_e32 v62, v62
	v_exp_f32_e32 v63, v63
	v_exp_f32_e32 v64, v64
	v_exp_f32_e32 v65, v65
	v_cvt_pk_bf16_f32 v192, v58, v59
	v_cvt_pk_bf16_f32 v193, v60, v61
	v_cvt_pk_bf16_f32 v194, v62, v63
	v_cvt_pk_bf16_f32 v195, v64, v65
	v_add_f32_e32 v130, v58, v59
	v_add_f32_e32 v131, v60, v61
	v_add_f32_e32 v130, v130, v62
	v_add_f32_e32 v131, v131, v63
	v_add_f32_e32 v130, v130, v64
	v_add_f32_e32 v131, v131, v65
	v_add_f32_e32 v97, v97, v130
	v_add_f32_e32 v97, v97, v131
	s_waitcnt lgkmcnt(2)
	v_mfma_f32_32x32x16_bf16 v[18:33], v[172:175], v[192:195], v[18:33]
	s_waitcnt lgkmcnt(0)
	v_mfma_f32_32x32x16_bf16 v[2:17], v[176:179], v[192:195], v[2:17]

.LBB0_283:
	s_andn2_b64 vcc, exec, s[10:11]
	s_cbranch_vccnz .LBB0_280
	s_add_i32 s10, s24, 0xffffc000
	s_and_b32 s10, s10, 0x4000
	v_add3_u32 v94, s10, v109, v108
	v_add3_u32 v95, s10, v110, v108
	v_add3_u32 v130, s10, v111, v108
	v_add3_u32 v131, s10, v112, v108
	ds_read_b128 v[148:151], v94
	ds_read_b128 v[152:155], v95
	ds_read_b128 v[156:159], v130
	ds_read_b128 v[160:163], v131
	ds_read_b128 v[164:167], v94 offset:4096
	ds_read_b128 v[168:171], v95 offset:4096
	ds_read_b128 v[172:175], v130 offset:4096
	ds_read_b128 v[176:179], v131 offset:4096
	s_andn2_b64 vcc, exec, s[72:73]
	s_waitcnt lgkmcnt(7)
	v_mfma_f32_32x32x16_bf16 v[34:49], v[148:151], v[78:81], 0
	s_waitcnt lgkmcnt(6)
	v_mfma_f32_32x32x16_bf16 v[34:49], v[152:155], v[74:77], v[34:49]
	s_waitcnt lgkmcnt(5)
	v_mfma_f32_32x32x16_bf16 v[34:49], v[156:159], v[70:73], v[34:49]
	s_waitcnt lgkmcnt(4)
	v_mfma_f32_32x32x16_bf16 v[34:49], v[160:163], v[66:69], v[34:49]
	s_waitcnt lgkmcnt(3)
	v_mfma_f32_32x32x16_bf16 v[50:65], v[164:167], v[78:81], 0
	s_waitcnt lgkmcnt(2)
	v_mfma_f32_32x32x16_bf16 v[50:65], v[168:171], v[74:77], v[50:65]
	s_waitcnt lgkmcnt(1)
	v_mfma_f32_32x32x16_bf16 v[50:65], v[172:175], v[70:73], v[50:65]
	s_waitcnt lgkmcnt(0)
	v_mfma_f32_32x32x16_bf16 v[50:65], v[176:179], v[66:69], v[50:65]
	s_cbranch_vccnz .LBB0_286
	v_cmp_ge_i32_e32 vcc, s3, v98
	v_cmp_lt_i32_e64 s[72:73], s3, v106
	s_and_b64 s[26:27], vcc, s[72:73]
	s_add_i32 s11, s3, 1
	v_cmp_ge_i32_e32 vcc, s11, v98
	v_cmp_lt_i32_e64 s[72:73], s11, v106
	s_and_b64 s[72:73], vcc, s[72:73]
	v_add_u32_e32 v94, s29, v125
	s_and_b64 vcc, s[26:27], s[68:69]
	v_add_u32_e32 v95, 0xffffff2f, v94
	v_cndmask_b32_e32 v95, 0, v95, vcc
	v_lshl_add_u32 v95, v95, 2, 0
	ds_read_b32 v148, v95 offset:32768
	s_and_b64 vcc, s[26:27], s[66:67]
	v_add_u32_e32 v95, 0xffffff30, v94
	v_cndmask_b32_e32 v95, 0, v95, vcc
	v_lshl_add_u32 v95, v95, 2, 0
	ds_read_b32 v149, v95 offset:32768
	s_and_b64 vcc, s[26:27], s[64:65]
	v_add_u32_e32 v95, 0xffffff31, v94
	v_cndmask_b32_e32 v95, 0, v95, vcc
	v_lshl_add_u32 v95, v95, 2, 0
	ds_read_b32 v150, v95 offset:32768
	s_and_b64 vcc, s[26:27], s[62:63]
	v_add_u32_e32 v95, 0xffffff32, v94
	v_cndmask_b32_e32 v95, 0, v95, vcc
	v_lshl_add_u32 v95, v95, 2, 0
	ds_read_b32 v151, v95 offset:32768
	s_and_b64 vcc, s[26:27], s[60:61]
	v_add_u32_e32 v95, 0xffffff37, v94
	v_cndmask_b32_e32 v95, 0, v95, vcc
	v_lshl_add_u32 v95, v95, 2, 0
	ds_read_b32 v152, v95 offset:32768
	s_and_b64 vcc, s[26:27], s[58:59]
	v_add_u32_e32 v95, 0xffffff38, v94
	v_cndmask_b32_e32 v95, 0, v95, vcc
	v_lshl_add_u32 v95, v95, 2, 0
	ds_read_b32 v153, v95 offset:32768
	s_and_b64 vcc, s[26:27], s[56:57]
	v_add_u32_e32 v95, 0xffffff39, v94
	v_cndmask_b32_e32 v95, 0, v95, vcc
	v_lshl_add_u32 v95, v95, 2, 0
	ds_read_b32 v154, v95 offset:32768
	s_and_b64 vcc, s[26:27], s[54:55]
	v_add_u32_e32 v95, 0xffffff3a, v94
	v_cndmask_b32_e32 v95, 0, v95, vcc
	v_lshl_add_u32 v95, v95, 2, 0
	ds_read_b32 v155, v95 offset:32768
	s_and_b64 vcc, s[26:27], s[52:53]
	v_add_u32_e32 v95, 0xffffff3f, v94
	v_cndmask_b32_e32 v95, 0, v95, vcc
	v_lshl_add_u32 v95, v95, 2, 0
	ds_read_b32 v156, v95 offset:32768
	s_and_b64 vcc, s[26:27], s[50:51]
	v_add_u32_e32 v95, 0xffffff40, v94
	v_cndmask_b32_e32 v95, 0, v95, vcc
	v_lshl_add_u32 v95, v95, 2, 0
	ds_read_b32 v157, v95 offset:32768
	s_and_b64 vcc, s[26:27], s[48:49]
	v_add_u32_e32 v95, 0xffffff41, v94
	v_cndmask_b32_e32 v95, 0, v95, vcc
	v_lshl_add_u32 v95, v95, 2, 0
	ds_read_b32 v158, v95 offset:32768
	s_and_b64 vcc, s[26:27], s[46:47]
	v_add_u32_e32 v95, 0xffffff42, v94
	v_cndmask_b32_e32 v95, 0, v95, vcc
	v_lshl_add_u32 v95, v95, 2, 0
	ds_read_b32 v159, v95 offset:32768
	s_waitcnt lgkmcnt(11)
	s_and_b64 vcc, s[26:27], s[68:69]
	v_add_f32_e32 v34, v34, v148
	v_cndmask_b32_e32 v34, v213, v34, vcc
	s_and_b64 vcc, s[26:27], s[44:45]
	v_add_u32_e32 v95, 0xffffff47, v94
	v_cndmask_b32_e32 v95, 0, v95, vcc
	v_lshl_add_u32 v95, v95, 2, 0
	ds_read_b32 v148, v95 offset:32768
	s_waitcnt lgkmcnt(11)
	s_and_b64 vcc, s[26:27], s[66:67]
	v_add_f32_e32 v35, v35, v149
	v_cndmask_b32_e32 v35, v213, v35, vcc
	s_and_b64 vcc, s[26:27], s[42:43]
	v_add_u32_e32 v95, 0xffffff48, v94
	v_cndmask_b32_e32 v95, 0, v95, vcc
	v_lshl_add_u32 v95, v95, 2, 0
	ds_read_b32 v149, v95 offset:32768
	s_waitcnt lgkmcnt(11)
	s_and_b64 vcc, s[26:27], s[64:65]
	v_add_f32_e32 v36, v36, v150
	v_cndmask_b32_e32 v36, v213, v36, vcc
	s_and_b64 vcc, s[26:27], s[40:41]
	v_add_u32_e32 v95, 0xffffff49, v94
	v_cndmask_b32_e32 v95, 0, v95, vcc
	v_lshl_add_u32 v95, v95, 2, 0
	ds_read_b32 v150, v95 offset:32768
	s_waitcnt lgkmcnt(11)
	s_and_b64 vcc, s[26:27], s[62:63]
	v_add_f32_e32 v37, v37, v151
	v_cndmask_b32_e32 v37, v213, v37, vcc
	s_and_b64 vcc, s[26:27], s[38:39]
	v_add_u32_e32 v95, 0xffffff4a, v94
	v_cndmask_b32_e32 v95, 0, v95, vcc
	v_lshl_add_u32 v95, v95, 2, 0
	ds_read_b32 v151, v95 offset:32768
	s_waitcnt lgkmcnt(11)
	s_and_b64 vcc, s[26:27], s[60:61]
	v_add_f32_e32 v38, v38, v152
	v_cndmask_b32_e32 v38, v213, v38, vcc
	s_and_b64 vcc, s[72:73], s[68:69]
	v_add_u32_e32 v95, 0xffffff4f, v94
	v_cndmask_b32_e32 v95, 0, v95, vcc
	v_lshl_add_u32 v95, v95, 2, 0
	ds_read_b32 v152, v95 offset:32768
	s_waitcnt lgkmcnt(11)
	s_and_b64 vcc, s[26:27], s[58:59]
	v_add_f32_e32 v39, v39, v153
	v_cndmask_b32_e32 v39, v213, v39, vcc
	s_and_b64 vcc, s[72:73], s[66:67]
	v_add_u32_e32 v95, 0xffffff50, v94
	v_cndmask_b32_e32 v95, 0, v95, vcc
	v_lshl_add_u32 v95, v95, 2, 0
	ds_read_b32 v153, v95 offset:32768
	s_waitcnt lgkmcnt(11)
	s_and_b64 vcc, s[26:27], s[56:57]
	v_add_f32_e32 v40, v40, v154
	v_cndmask_b32_e32 v40, v213, v40, vcc
	s_and_b64 vcc, s[72:73], s[64:65]
	v_add_u32_e32 v95, 0xffffff51, v94
	v_cndmask_b32_e32 v95, 0, v95, vcc
	v_lshl_add_u32 v95, v95, 2, 0
	ds_read_b32 v154, v95 offset:32768
	s_waitcnt lgkmcnt(11)
	s_and_b64 vcc, s[26:27], s[54:55]
	v_add_f32_e32 v41, v41, v155
	v_cndmask_b32_e32 v41, v213, v41, vcc
	s_and_b64 vcc, s[72:73], s[62:63]
	v_add_u32_e32 v95, 0xffffff52, v94
	v_cndmask_b32_e32 v95, 0, v95, vcc
	v_lshl_add_u32 v95, v95, 2, 0
	ds_read_b32 v155, v95 offset:32768
	s_waitcnt lgkmcnt(11)
	s_and_b64 vcc, s[26:27], s[52:53]
	v_add_f32_e32 v42, v42, v156
	v_cndmask_b32_e32 v42, v213, v42, vcc
	s_and_b64 vcc, s[72:73], s[60:61]
	v_add_u32_e32 v95, 0xffffff57, v94
	v_cndmask_b32_e32 v95, 0, v95, vcc
	v_lshl_add_u32 v95, v95, 2, 0
	ds_read_b32 v156, v95 offset:32768
	s_waitcnt lgkmcnt(11)
	s_and_b64 vcc, s[26:27], s[50:51]
	v_add_f32_e32 v43, v43, v157
	v_cndmask_b32_e32 v43, v213, v43, vcc
	s_and_b64 vcc, s[72:73], s[58:59]
	v_add_u32_e32 v95, 0xffffff58, v94
	v_cndmask_b32_e32 v95, 0, v95, vcc
	v_lshl_add_u32 v95, v95, 2, 0
	ds_read_b32 v157, v95 offset:32768
	s_waitcnt lgkmcnt(11)
	s_and_b64 vcc, s[26:27], s[48:49]
	v_add_f32_e32 v44, v44, v158
	v_cndmask_b32_e32 v44, v213, v44, vcc
	s_and_b64 vcc, s[72:73], s[56:57]
	v_add_u32_e32 v95, 0xffffff59, v94
	v_cndmask_b32_e32 v95, 0, v95, vcc
	v_lshl_add_u32 v95, v95, 2, 0
	ds_read_b32 v158, v95 offset:32768
	s_waitcnt lgkmcnt(11)
	s_and_b64 vcc, s[26:27], s[46:47]
	v_add_f32_e32 v45, v45, v159
	v_cndmask_b32_e32 v45, v213, v45, vcc
	s_and_b64 vcc, s[72:73], s[54:55]
	v_add_u32_e32 v95, 0xffffff5a, v94
	v_cndmask_b32_e32 v95, 0, v95, vcc
	v_lshl_add_u32 v95, v95, 2, 0
	ds_read_b32 v159, v95 offset:32768
	s_waitcnt lgkmcnt(11)
	s_and_b64 vcc, s[26:27], s[44:45]
	v_add_f32_e32 v46, v46, v148
	v_cndmask_b32_e32 v46, v213, v46, vcc
	s_and_b64 vcc, s[72:73], s[52:53]
	v_add_u32_e32 v95, 0xffffff5f, v94
	v_cndmask_b32_e32 v95, 0, v95, vcc
	v_lshl_add_u32 v95, v95, 2, 0
	ds_read_b32 v148, v95 offset:32768
	s_waitcnt lgkmcnt(11)
	s_and_b64 vcc, s[26:27], s[42:43]
	v_add_f32_e32 v47, v47, v149
	v_cndmask_b32_e32 v47, v213, v47, vcc
	s_and_b64 vcc, s[72:73], s[50:51]
	v_add_u32_e32 v95, 0xffffff60, v94
	v_cndmask_b32_e32 v95, 0, v95, vcc
	v_lshl_add_u32 v95, v95, 2, 0
	ds_read_b32 v149, v95 offset:32768
	s_waitcnt lgkmcnt(11)
	s_and_b64 vcc, s[26:27], s[40:41]
	v_add_f32_e32 v48, v48, v150
	v_cndmask_b32_e32 v48, v213, v48, vcc
	s_and_b64 vcc, s[72:73], s[48:49]
	v_add_u32_e32 v95, 0xffffff61, v94
	v_cndmask_b32_e32 v95, 0, v95, vcc
	v_lshl_add_u32 v95, v95, 2, 0
	ds_read_b32 v150, v95 offset:32768
	s_waitcnt lgkmcnt(11)
	s_and_b64 vcc, s[26:27], s[38:39]
	v_add_f32_e32 v49, v49, v151
	v_cndmask_b32_e32 v49, v213, v49, vcc
	s_and_b64 vcc, s[72:73], s[46:47]
	v_add_u32_e32 v95, 0xffffff62, v94
	v_cndmask_b32_e32 v95, 0, v95, vcc
	v_lshl_add_u32 v95, v95, 2, 0
	ds_read_b32 v151, v95 offset:32768
	s_waitcnt lgkmcnt(11)
	s_and_b64 vcc, s[72:73], s[68:69]
	v_add_f32_e32 v50, v50, v152
	v_cndmask_b32_e32 v50, v213, v50, vcc
	s_and_b64 vcc, s[72:73], s[44:45]
	v_add_u32_e32 v95, 0xffffff67, v94
	v_cndmask_b32_e32 v95, 0, v95, vcc
	v_lshl_add_u32 v95, v95, 2, 0
	ds_read_b32 v152, v95 offset:32768
	s_waitcnt lgkmcnt(11)
	s_and_b64 vcc, s[72:73], s[66:67]
	v_add_f32_e32 v51, v51, v153
	v_cndmask_b32_e32 v51, v213, v51, vcc
	s_and_b64 vcc, s[72:73], s[42:43]
	v_add_u32_e32 v95, 0xffffff68, v94
	v_cndmask_b32_e32 v95, 0, v95, vcc
	v_lshl_add_u32 v95, v95, 2, 0
	ds_read_b32 v153, v95 offset:32768
	s_waitcnt lgkmcnt(11)
	s_and_b64 vcc, s[72:73], s[64:65]
	v_add_f32_e32 v52, v52, v154
	v_cndmask_b32_e32 v52, v213, v52, vcc
	s_and_b64 vcc, s[72:73], s[40:41]
	v_add_u32_e32 v95, 0xffffff69, v94
	v_cndmask_b32_e32 v95, 0, v95, vcc
	v_lshl_add_u32 v95, v95, 2, 0
	ds_read_b32 v154, v95 offset:32768
	s_waitcnt lgkmcnt(11)
	s_and_b64 vcc, s[72:73], s[62:63]
	v_add_f32_e32 v53, v53, v155
	v_cndmask_b32_e32 v53, v213, v53, vcc
	s_and_b64 vcc, s[72:73], s[38:39]
	v_add_u32_e32 v95, 0xffffff6a, v94
	v_cndmask_b32_e32 v95, 0, v95, vcc
	v_lshl_add_u32 v95, v95, 2, 0
	ds_read_b32 v155, v95 offset:32768
	s_waitcnt lgkmcnt(11)
	s_and_b64 vcc, s[72:73], s[60:61]
	v_add_f32_e32 v54, v54, v156
	v_cndmask_b32_e32 v54, v213, v54, vcc
	s_waitcnt lgkmcnt(10)
	s_and_b64 vcc, s[72:73], s[58:59]
	v_add_f32_e32 v55, v55, v157
	v_cndmask_b32_e32 v55, v213, v55, vcc
	s_waitcnt lgkmcnt(9)
	s_and_b64 vcc, s[72:73], s[56:57]
	v_add_f32_e32 v56, v56, v158
	v_cndmask_b32_e32 v56, v213, v56, vcc
	s_waitcnt lgkmcnt(8)
	s_and_b64 vcc, s[72:73], s[54:55]
	v_add_f32_e32 v57, v57, v159
	v_cndmask_b32_e32 v57, v213, v57, vcc
	s_waitcnt lgkmcnt(7)
	s_and_b64 vcc, s[72:73], s[52:53]
	v_add_f32_e32 v58, v58, v148
	v_cndmask_b32_e32 v58, v213, v58, vcc
	s_waitcnt lgkmcnt(6)
	s_and_b64 vcc, s[72:73], s[50:51]
	v_add_f32_e32 v59, v59, v149
	v_cndmask_b32_e32 v59, v213, v59, vcc
	s_waitcnt lgkmcnt(5)
	s_and_b64 vcc, s[72:73], s[48:49]
	v_add_f32_e32 v60, v60, v150
	v_cndmask_b32_e32 v60, v213, v60, vcc
	s_waitcnt lgkmcnt(4)
	s_and_b64 vcc, s[72:73], s[46:47]
	v_add_f32_e32 v61, v61, v151
	v_cndmask_b32_e32 v61, v213, v61, vcc
	s_waitcnt lgkmcnt(3)
	s_and_b64 vcc, s[72:73], s[44:45]
	v_add_f32_e32 v62, v62, v152
	v_cndmask_b32_e32 v62, v213, v62, vcc
	s_waitcnt lgkmcnt(2)
	s_and_b64 vcc, s[72:73], s[42:43]
	v_add_f32_e32 v63, v63, v153
	v_cndmask_b32_e32 v63, v213, v63, vcc
	s_waitcnt lgkmcnt(1)
	s_and_b64 vcc, s[72:73], s[40:41]
	v_add_f32_e32 v64, v64, v154
	v_cndmask_b32_e32 v64, v213, v64, vcc
	s_waitcnt lgkmcnt(0)
	s_and_b64 vcc, s[72:73], s[38:39]
	v_add_f32_e32 v65, v65, v155
	v_cndmask_b32_e32 v65, v213, v65, vcc
.LBB0_286:
	s_nop 10
	v_max3_f32 v94, v34, v35, v36
	v_max3_f32 v94, v94, v37, v38
	v_max3_f32 v94, v94, v39, v40
	v_max3_f32 v94, v94, v41, v42
	v_max3_f32 v94, v94, v43, v44
	v_max3_f32 v94, v94, v45, v46
	v_max3_f32 v94, v94, v47, v48
	v_max3_f32 v95, v50, v51, v52
	v_max3_f32 v95, v95, v53, v54
	v_max3_f32 v95, v95, v55, v56
	v_max3_f32 v95, v95, v57, v58
	v_max3_f32 v95, v95, v59, v60
	v_max3_f32 v95, v95, v61, v62
	v_max3_f32 v95, v95, v63, v64
	v_max3_f32 v94, v94, v95, v49
	v_max_f32_e32 v94, v94, v65
	v_mov_b32_e32 v95, v94
	s_nop 1
	v_permlane32_swap_b32_e32 v94, v95
	v_max_f32_e32 v95, v95, v95
	v_max_f32_e32 v94, v94, v94
	v_max_f32_e32 v94, v94, v95
	v_sub_f32_e32 v95, v94, v101
	s_mov_b32 s2, 0x41000000
	v_cmp_ge_f32_e32 vcc, s2, v95
	s_cmp_eq_u64 vcc, exec
	s_cbranch_scc1 .LBB0_279
	v_max_f32_e32 v94, v94, v94
	v_max_f32_e32 v95, v101, v101
	v_max_f32_e32 v95, v95, v94
	v_sub_f32_e32 v94, v101, v95
	v_exp_f32_e32 v94, v94
	v_mov_b32_e32 v101, v95
	v_pk_mul_f32 v[32:33], v[32:33], v[94:95] op_sel_hi:[1,0]
	v_pk_mul_f32 v[30:31], v[30:31], v[94:95] op_sel_hi:[1,0]
	v_pk_mul_f32 v[28:29], v[28:29], v[94:95] op_sel_hi:[1,0]
	v_pk_mul_f32 v[26:27], v[26:27], v[94:95] op_sel_hi:[1,0]
	v_pk_mul_f32 v[24:25], v[24:25], v[94:95] op_sel_hi:[1,0]
	v_pk_mul_f32 v[22:23], v[22:23], v[94:95] op_sel_hi:[1,0]
	v_pk_mul_f32 v[20:21], v[20:21], v[94:95] op_sel_hi:[1,0]
	v_pk_mul_f32 v[18:19], v[18:19], v[94:95] op_sel_hi:[1,0]
	v_pk_mul_f32 v[16:17], v[16:17], v[94:95] op_sel_hi:[1,0]
	v_pk_mul_f32 v[14:15], v[14:15], v[94:95] op_sel_hi:[1,0]
	v_pk_mul_f32 v[12:13], v[12:13], v[94:95] op_sel_hi:[1,0]
	v_pk_mul_f32 v[10:11], v[10:11], v[94:95] op_sel_hi:[1,0]
	v_pk_mul_f32 v[8:9], v[8:9], v[94:95] op_sel_hi:[1,0]
	v_pk_mul_f32 v[6:7], v[6:7], v[94:95] op_sel_hi:[1,0]
	v_pk_mul_f32 v[4:5], v[4:5], v[94:95] op_sel_hi:[1,0]
	v_pk_mul_f32 v[2:3], v[2:3], v[94:95] op_sel_hi:[1,0]
	v_mul_f32_e32 v97, v97, v94
	s_branch .LBB0_279
